# grid barrier: runtime-verified XCD-local barriers at seams P1-P2, P5-P6, P7-P8 (row panels never leave an XCD there), early L1/L2 invalidate overlapped with the wait
# speedup vs baseline: 1.0257x; 1.0199x over previous
; #define LAS __attribute__((address_space(3)))
; __device__ __forceinline__ unsigned xb_add(unsigned* p, unsigned v) { return __hip_atomic_fetch_add(p, v, __ATOMIC_RELAXED, __HIP_MEMORY_SCOPE_AGENT); }
; __device__ __forceinline__ unsigned xb_xcc_id() { return (unsigned)__builtin_amdgcn_s_getreg((3 << 11) | 20) & 0xFu; }
; __device__ __forceinline__ XcdBarrier xcd_barrier_post(unsigned* bar, volatile LAS unsigned* st) {
;     XcdBarrier b; b.bar = bar; b.x = xb_xcc_id(); b.st = st;
;     if (threadIdx.x == 0) (void)xb_add(&bar[XB_XCNT(b.x)], 1u);
;     return b;
; }
; __global__ void __launch_bounds__(NTHREADS, 2) mega_fwd(Args a) {
;     extern __shared__ __attribute__((aligned(16))) unsigned char lds_raw[];
;     LAS unsigned char* lds = (LAS unsigned char*)lds_raw;
;     const int G = gridDim.x;
;     unsigned char* ws = a.ws;
;     const int lo = a.ph_lo, hi = a.ph_hi;
;     volatile LAS unsigned* MISC = (volatile LAS unsigned*)(lds + MISC_OFF);
;     if (threadIdx.x < 32) MISC[threadIdx.x] = 0u;
;     __syncthreads();
;     XcdBarrier bar; bar.bar = (unsigned*)(ws + WS_BAR); bar.x = 0; bar.st = nullptr;
;     if (hi - lo > 1) bar = xcd_barrier_post((unsigned*)(ws + WS_BAR), MISC + 8);
_Z8mega_fwd4Args:
	s_load_dword s11, s[0:1], 0x160
	s_load_dwordx2 s[28:29], s[0:1], 0xc8
	s_load_dwordx2 s[30:31], s[0:1], 0x150
	s_add_u32 s34, s0, 0x160
	v_and_b32_e32 v198, 0x3ff, v0
	s_mov_b32 s10, s2
	s_addc_u32 s35, s1, 0
	v_cmp_gt_u32_e32 vcc, 32, v198
	s_and_saveexec_b64 s[2:3], vcc
	v_lshl_add_u32 v1, v198, 2, 0
	v_add_u32_e32 v1, 0x20140, v1
	v_mov_b32_e32 v2, 0
	ds_write_b32 v1, v2
	s_or_b64 exec, exec, s[2:3]
	s_waitcnt lgkmcnt(0)
	s_add_u32 s60, s28, 0x80000
	s_addc_u32 s61, s29, 0
	s_sub_i32 s2, s31, s30
	s_cmp_lt_i32 s2, 2
	s_cselect_b64 s[76:77], -1, 0
	s_mov_b32 s33, 0
	s_and_b64 vcc, exec, s[76:77]
	s_mov_b32 s79, 0
	s_barrier
	s_cbranch_vccnz .LBB0_7
	s_getreg_b32 s2, hwreg(HW_REG_XCC_ID, 0, 4)
	s_and_b32 s33, s2, 15
	v_cmp_eq_u32_e32 vcc, 0, v198
	s_and_saveexec_b64 s[2:3], vcc
	s_cbranch_execz .LBB0_6
	s_mov_b64 s[4:5], exec
	v_mbcnt_lo_u32_b32 v1, s4, 0
	v_mbcnt_hi_u32_b32 v1, s5, v1
	v_cmp_eq_u32_e32 vcc, 0, v1
	s_and_b64 s[6:7], exec, vcc
	s_mov_b64 exec, s[6:7]
	s_cbranch_execz .LBB0_6
	s_lshl_b32 s6, s33, 8
	s_bcnt1_i32_b64 s4, s[4:5]
	v_mov_b32_e32 v1, s6
	v_mov_b32_e32 v2, s4
	global_atomic_add v1, v2, s[60:61] offset:1024
	s_and_b32 s4, s10, 7
	s_lshl_b32 s4, s4, 2
	s_add_i32 s4, s4, 0x4000
	s_lshl_b32 s6, 1, s33
	v_mov_b32_e32 v3, s4
	v_mov_b32_e32 v4, s6
	global_atomic_or v3, v4, s[60:61]

; __device__ __forceinline__ unsigned xb_ld(unsigned* p)              { return __hip_atomic_load(p, __ATOMIC_RELAXED, __HIP_MEMORY_SCOPE_AGENT); }
; __device__ __forceinline__ unsigned xb_add(unsigned* p, unsigned v) { return __hip_atomic_fetch_add(p, v, __ATOMIC_RELAXED, __HIP_MEMORY_SCOPE_AGENT); }
; #define XB_SPIN(cond, bar) do { unsigned _sp = 0; while (cond) { __builtin_amdgcn_s_sleep(1); \
;     if ((++_sp & 255u) == 0u) { if (xb_ld(&(bar)[XB_TMO])) break; if (_sp > XB_SPIN_CAP) { atomicAdd(&(bar)[XB_TMO], 1u); break; } } } } while (0)
; __device__ __forceinline__ void xcd_barrier(const XcdBarrier& b) {
;     ...
;     if (threadIdx.x == 0) {
;         unsigned* bar = b.bar;
;         __builtin_amdgcn_s_waitcnt(0);
;         unsigned nloc = b.st[0], nx = b.st[1];
;         if (nloc == 0u) { xcd_barrier_complete(bar, b.x, nloc, nx); b.st[0] = nloc; b.st[1] = nx; }
;         const unsigned old = xb_add(&bar[XB_XSUB(b.x)], 1u);
;         const unsigned gen = old / nloc;
;         if (old + 1u == (gen + 1u) * nloc) {
;             __builtin_amdgcn_fence(__ATOMIC_RELEASE, "agent");
;             asm volatile("s_waitcnt vmcnt(0)" ::: "memory");
;             const unsigned og = xb_add(&bar[XB_TOP], 1u);
;             const unsigned tg = og / nx;
;             if (og + 1u == (tg + 1u) * nx) xb_add(&bar[XB_TOPGEN], 1u);
;             else XB_SPIN(xb_ld(&bar[XB_TOPGEN]) == tg, bar);
;             __builtin_amdgcn_fence(__ATOMIC_ACQUIRE, "agent");
;             xb_add(&bar[XB_XGEN(b.x)], 1u);
;             asm volatile("s_waitcnt vmcnt(0)" ::: "memory");
;         } else {
;             XB_SPIN(xb_ld(&bar[XB_XGEN(b.x)]) == gen, bar);
.LBB0_203:
	s_lshl_b32 s4, s33, 8
	s_add_u32 s4, s60, s4
	s_addc_u32 s5, s61, 0
	v_mov_b32_e32 v2, 0x1000
	v_mov_b32_e32 v4, 1
	global_atomic_add v4, v2, v4, s[4:5] offset:1024 sc0
	v_cvt_f32_u32_e32 v2, v3
	v_sub_u32_e32 v5, 0, v3
	v_rcp_iflag_f32_e32 v2, v2
	s_nop 0
	v_mul_f32_e32 v2, 0x4f7ffffe, v2
	v_cvt_u32_f32_e32 v2, v2
	v_mul_lo_u32 v5, v5, v2
	v_mul_hi_u32 v5, v2, v5
	v_add_u32_e32 v2, v2, v5
	s_waitcnt vmcnt(0)
	v_mul_hi_u32 v2, v4, v2
	v_mul_lo_u32 v5, v2, v3
	v_sub_u32_e32 v5, v4, v5
	v_add_u32_e32 v6, 1, v2
	v_cmp_ge_u32_e32 vcc, v5, v3
	v_add_u32_e32 v4, 1, v4
	s_nop 0
	v_cndmask_b32_e32 v2, v2, v6, vcc
	v_sub_u32_e32 v6, v5, v3
	v_cndmask_b32_e32 v5, v5, v6, vcc
	v_add_u32_e32 v6, 1, v2
	v_cmp_ge_u32_e32 vcc, v5, v3
	s_nop 1
	v_cndmask_b32_e32 v2, v2, v6, vcc
	v_mul_lo_u32 v5, v3, v2
	v_add_u32_e32 v3, v5, v3
	v_cmp_ne_u32_e32 vcc, v4, v3
	s_and_saveexec_b64 s[6:7], vcc
	s_xor_b64 s[6:7], exec, s[6:7]
	s_cbranch_execz .LBB0_217
	s_waitcnt lgkmcnt(0)
	buffer_inv sc1
	v_mov_b32_e32 v1, 0x2000
	global_load_dword v1, v1, s[4:5] offset:1024 sc1
	s_add_u32 s14, s4, 0x2400
	s_addc_u32 s15, s5, 0
	s_waitcnt vmcnt(0)
	v_cmp_eq_u32_e32 vcc, v1, v2
	s_and_saveexec_b64 s[8:9], vcc
	s_cbranch_execz .LBB0_216
	s_add_u32 s12, s28, 0x80200
	s_addc_u32 s13, s29, 0
	s_mov_b32 s26, 1
	s_mov_b64 s[16:17], 0
	v_mov_b32_e32 v1, 0
	s_branch .LBB0_207

; __device__ __forceinline__ unsigned xb_ld(unsigned* p)              { return __hip_atomic_load(p, __ATOMIC_RELAXED, __HIP_MEMORY_SCOPE_AGENT); }
; __device__ __forceinline__ unsigned xb_add(unsigned* p, unsigned v) { return __hip_atomic_fetch_add(p, v, __ATOMIC_RELAXED, __HIP_MEMORY_SCOPE_AGENT); }
; #define XB_SPIN(cond, bar) do { unsigned _sp = 0; while (cond) { __builtin_amdgcn_s_sleep(1); \
;     if ((++_sp & 255u) == 0u) { if (xb_ld(&(bar)[XB_TMO])) break; if (_sp > XB_SPIN_CAP) { atomicAdd(&(bar)[XB_TMO], 1u); break; } } } } while (0)
; __device__ __forceinline__ void xcd_barrier(const XcdBarrier& b) {
;     ...
;         const unsigned old = xb_add(&bar[XB_XSUB(b.x)], 1u);
;         const unsigned gen = old / nloc;
;         if (old + 1u == (gen + 1u) * nloc) {
;             __builtin_amdgcn_fence(__ATOMIC_RELEASE, "agent");
;             asm volatile("s_waitcnt vmcnt(0)" ::: "memory");
;             const unsigned og = xb_add(&bar[XB_TOP], 1u);
;             const unsigned tg = og / nx;
;             if (og + 1u == (tg + 1u) * nx) xb_add(&bar[XB_TOPGEN], 1u);
;             else XB_SPIN(xb_ld(&bar[XB_TOPGEN]) == tg, bar);
;             __builtin_amdgcn_fence(__ATOMIC_ACQUIRE, "agent");
;             xb_add(&bar[XB_XGEN(b.x)], 1u);
.LBB0_216:
	s_or_b64 exec, exec, s[8:9]
	s_waitcnt vmcnt(0)
	s_waitcnt vmcnt(0)
.LBB0_217:
	s_andn2_saveexec_b64 s[6:7], s[6:7]
	s_cbranch_execz .LBB0_235
	s_mov_b64 s[6:7], exec
	buffer_inv sc1
	buffer_wbl2 sc1
	s_waitcnt lgkmcnt(0)
	s_waitcnt vmcnt(0)
	v_mbcnt_lo_u32_b32 v2, s6, 0
	v_mbcnt_hi_u32_b32 v2, s7, v2
	v_cmp_eq_u32_e32 vcc, 0, v2
	s_and_saveexec_b64 s[8:9], vcc
	s_cbranch_execz .LBB0_220
	s_bcnt1_i32_b64 s6, s[6:7]
	v_mov_b32_e32 v3, 0x83000
	v_mov_b32_e32 v4, s6
	global_atomic_add v3, v3, v4, s[28:29] offset:1024 sc0

; __device__ __forceinline__ unsigned xb_add(unsigned* p, unsigned v) { return __hip_atomic_fetch_add(p, v, __ATOMIC_RELAXED, __HIP_MEMORY_SCOPE_AGENT); }
; __device__ __forceinline__ void xcd_barrier(const XcdBarrier& b) {
;     ...
;             __builtin_amdgcn_fence(__ATOMIC_ACQUIRE, "agent");
;             xb_add(&bar[XB_XGEN(b.x)], 1u);
;             asm volatile("s_waitcnt vmcnt(0)" ::: "memory");
.LBB0_234:
	s_or_b64 exec, exec, s[6:7]
	v_mov_b32_e32 v1, 0x2000
	v_mov_b32_e32 v2, 1
	s_waitcnt vmcnt(0)
	global_atomic_add v1, v2, s[4:5] offset:1024
	s_waitcnt vmcnt(0)

; #define SEAM(k) do { if (IN(k) && IN((k) + 1)) { if (lo < 0) cg::this_grid().sync(); else xcd_barrier(bar); } } while (0)
;     __device__ bool next(int i, Unit& u) const {
;         long L = (long)i * G + c; u.half = 0;
;         if (split) { const int fr_ = nwg / G, rem = nwg - fr_ * G; if (i > fr_) return false; if (i == fr_) { L = (long)fr_ * G + (c % rem); u.half = 1 + c / rem; } }
;         if (L >= nwg) return false;
;         int wgid = (int)L; { const int q = nwg / NXCD, r = nwg % NXCD, xcd = wgid % NXCD, off = wgid / NXCD; wgid = (xcd < r ? xcd * (q + 1) : r * (q + 1) + (xcd - r) * q) + off; }
;         const int nig = WGM * nN, gid = wgid / nig, fm = gid * WGM, gsz = (nM - fm) < WGM ? (nM - fm) : WGM;
;         u.pm = fm + ((wgid % nig) % gsz); u.pn = (wgid % nig) / gsz; return true;
; __global__ void __launch_bounds__(NTHREADS, 2) mega_fwd(Args a) {
;     ...
;     const bool late_in_p1 = (G == 256) && IN(0) && IN(1);
;     if (IN(0)) { for (int rep = 0; rep < a.rep0; ++rep) p0_prologue(a, lds, G, late_in_p1); SEAM(0); }
;     if (IN(1)) {
;         if ((int)blockIdx.x >= G - 2) {
;             pg8::Gemm g{(const bf16_t*)(ws + WS_MEMN), (const bf16_t*)(ws + WS_WMKV), D, D, D, MEML, 512}; pg8::StaticOrder so; so.init(MEML, 512, 2, (int)blockIdx.x - (G - 2));
;             pg8::Epi E{}; E.mode = pg8::M_MEMKV; E.O = (bf16_t*)(ws + WS_KV); E.gains = (const float*)(ws + WS_GAINS);
;             pg8::gemm_phase(lds, g, so, E);
;         }
;         pg8::Gemm g{XB, (const bf16_t*)(ws + WS_W13_1), D, D, D, S, 2 * FF}; pg8::StaticOrder so; so.init(S, 2 * FF, G, (int)blockIdx.x);
.LBB0_249:
	s_mov_b32 s98, 1
	s_mov_b32 s99, 0
	s_load_dword s100, s[28:29], 0x84000
	s_waitcnt lgkmcnt(0)
	s_bcnt1_i32_b32 s101, s100
	s_cmp_eq_u32 s101, 1
	s_cselect_b32 s98, s98, 0
	s_or_b32 s99, s99, s100
	s_load_dword s100, s[28:29], 0x84004
	s_waitcnt lgkmcnt(0)
	s_bcnt1_i32_b32 s101, s100
	s_cmp_eq_u32 s101, 1
	s_cselect_b32 s98, s98, 0
	s_or_b32 s99, s99, s100
	s_load_dword s100, s[28:29], 0x84008
	s_waitcnt lgkmcnt(0)
	s_bcnt1_i32_b32 s101, s100
	s_cmp_eq_u32 s101, 1
	s_cselect_b32 s98, s98, 0
	s_or_b32 s99, s99, s100
	s_load_dword s100, s[28:29], 0x8400c
	s_waitcnt lgkmcnt(0)
	s_bcnt1_i32_b32 s101, s100
	s_cmp_eq_u32 s101, 1
	s_cselect_b32 s98, s98, 0
	s_or_b32 s99, s99, s100
	s_load_dword s100, s[28:29], 0x84010
	s_waitcnt lgkmcnt(0)
	s_bcnt1_i32_b32 s101, s100
	s_cmp_eq_u32 s101, 1
	s_cselect_b32 s98, s98, 0
	s_or_b32 s99, s99, s100
	s_load_dword s100, s[28:29], 0x84014
	s_waitcnt lgkmcnt(0)
	s_bcnt1_i32_b32 s101, s100
	s_cmp_eq_u32 s101, 1
	s_cselect_b32 s98, s98, 0
	s_or_b32 s99, s99, s100
	s_load_dword s100, s[28:29], 0x84018
	s_waitcnt lgkmcnt(0)
	s_bcnt1_i32_b32 s101, s100
	s_cmp_eq_u32 s101, 1
	s_cselect_b32 s98, s98, 0
	s_or_b32 s99, s99, s100
	s_load_dword s100, s[28:29], 0x8401c
	s_waitcnt lgkmcnt(0)
	s_bcnt1_i32_b32 s101, s100
	s_cmp_eq_u32 s101, 1
	s_cselect_b32 s98, s98, 0
	s_or_b32 s99, s99, s100
	s_bcnt1_i32_b32 s101, s99
	s_cmp_eq_u32 s101, 8
	s_cselect_b32 s98, s98, 0
	s_add_u32 s8, s28, 0x3600000
	s_addc_u32 s9, s29, 0
	s_add_u32 s20, s28, 0x5600000
	s_addc_u32 s21, s29, 0
	s_cmp_lt_i32 s30, 2
	s_cselect_b64 s[2:3], -1, 0
	s_and_b64 s[2:3], s[2:3], s[68:69]
	s_andn2_b64 vcc, exec, s[2:3]
	s_cbranch_vccnz .LBB0_457
	s_add_i32 s2, s11, -2
	s_cmp_ge_i32 s10, s2
	s_cbranch_scc0 .LBB0_292
	s_add_u32 s4, s28, 0xdb00000
	s_addc_u32 s5, s29, 0
	s_add_u32 s6, s28, 0xdc00000
	s_addc_u32 s7, s29, 0
	s_sub_i32 s74, s10, s2
	s_cmp_lt_i32 s74, 2
	v_readfirstlane_b32 s12, v198
	s_mov_b64 s[14:15], 0
	s_mov_b64 s[16:17], 0
	s_mov_b64 s[18:19], 0
	s_mov_b64 s[22:23], 0
	s_cselect_b64 s[2:3], -1, 0
	s_cmp_gt_i32 s74, 1
	s_cbranch_scc1 .LBB0_253
	s_ashr_i32 s13, s74, 31
	s_lshr_b32 s13, s13, 29
	s_add_i32 s13, s74, s13
	s_ashr_i32 s14, s13, 3
	s_and_b32 s13, s13, -8
	s_sub_i32 s13, s74, s13
	s_add_i32 s13, s13, s14
	s_ashr_i32 s14, s13, 31
	s_lshr_b32 s14, s14, 28
	s_add_i32 s14, s13, s14
	s_ashr_i32 s14, s14, 4
	s_lshl_b32 s16, s14, 3
	s_sub_i32 s15, 1, s16
	s_lshl_b32 s14, s14, 4
	s_min_u32 s17, s15, 8
	s_sub_i32 s13, s13, s14
	s_sext_i32_i8 s14, s13
	s_waitcnt vmcnt(4)
	v_cvt_f32_ubyte0_e32 v2, s17
	v_cvt_f32_i32_e32 v1, s14
	v_rcp_iflag_f32_e32 v3, v2
	s_ashr_i32 s14, s14, 30
	s_or_b32 s18, s14, 1
	v_mul_f32_e32 v3, v1, v3
	v_trunc_f32_e32 v3, v3
	v_fma_f32 v1, -v3, v2, v1
	v_cvt_i32_f32_e32 v3, v3
	v_cmp_ge_f32_e64 s[14:15], |v1|, v2
	s_and_b64 s[14:15], s[14:15], exec
	s_cselect_b32 s14, s18, 0
	v_readfirstlane_b32 s15, v3
	s_add_i32 s14, s15, s14
	s_sext_i32_i8 s68, s14
	s_mul_i32 s14, s14, s17
	s_sub_i32 s13, s13, s14
	s_sext_i32_i8 s13, s13
	s_add_i32 s58, s16, s13

; __device__ __forceinline__ unsigned xb_ld(unsigned* p)              { return __hip_atomic_load(p, __ATOMIC_RELAXED, __HIP_MEMORY_SCOPE_AGENT); }
; __device__ __forceinline__ unsigned xb_add(unsigned* p, unsigned v) { return __hip_atomic_fetch_add(p, v, __ATOMIC_RELAXED, __HIP_MEMORY_SCOPE_AGENT); }
; #define XB_SPIN(cond, bar) do { unsigned _sp = 0; while (cond) { __builtin_amdgcn_s_sleep(1); \
;     if ((++_sp & 255u) == 0u) { if (xb_ld(&(bar)[XB_TMO])) break; if (_sp > XB_SPIN_CAP) { atomicAdd(&(bar)[XB_TMO], 1u); break; } } } } while (0)
; __device__ __forceinline__ void xcd_barrier(const XcdBarrier& b) {
;     ...
;     if (threadIdx.x == 0) {
;         unsigned* bar = b.bar;
;         __builtin_amdgcn_s_waitcnt(0);
;         unsigned nloc = b.st[0], nx = b.st[1];
;         if (nloc == 0u) { xcd_barrier_complete(bar, b.x, nloc, nx); b.st[0] = nloc; b.st[1] = nx; }
;         const unsigned old = xb_add(&bar[XB_XSUB(b.x)], 1u);
;         const unsigned gen = old / nloc;
;         if (old + 1u == (gen + 1u) * nloc) {
;             __builtin_amdgcn_fence(__ATOMIC_RELEASE, "agent");
;             asm volatile("s_waitcnt vmcnt(0)" ::: "memory");
;             const unsigned og = xb_add(&bar[XB_TOP], 1u);
;             const unsigned tg = og / nx;
;             if (og + 1u == (tg + 1u) * nx) xb_add(&bar[XB_TOPGEN], 1u);
;             else XB_SPIN(xb_ld(&bar[XB_TOPGEN]) == tg, bar);
;             __builtin_amdgcn_fence(__ATOMIC_ACQUIRE, "agent");
;             xb_add(&bar[XB_XGEN(b.x)], 1u);
;             asm volatile("s_waitcnt vmcnt(0)" ::: "memory");
;         } else {
;             XB_SPIN(xb_ld(&bar[XB_XGEN(b.x)]) == gen, bar);
.LBB0_411:
	s_lshl_b32 s4, s33, 8
	s_add_u32 s4, s60, s4
	s_addc_u32 s5, s61, 0
	v_mov_b32_e32 v2, 0x1000
	v_mov_b32_e32 v4, 1
	global_atomic_add v4, v2, v4, s[4:5] offset:1024 sc0
	v_cvt_f32_u32_e32 v2, v3
	v_sub_u32_e32 v5, 0, v3
	v_rcp_iflag_f32_e32 v2, v2
	s_nop 0
	v_mul_f32_e32 v2, 0x4f7ffffe, v2
	v_cvt_u32_f32_e32 v2, v2
	v_mul_lo_u32 v5, v5, v2
	v_mul_hi_u32 v5, v2, v5
	v_add_u32_e32 v2, v2, v5
	s_waitcnt vmcnt(0)
	v_mul_hi_u32 v2, v4, v2
	v_mul_lo_u32 v5, v2, v3
	v_sub_u32_e32 v5, v4, v5
	v_add_u32_e32 v6, 1, v2
	v_cmp_ge_u32_e32 vcc, v5, v3
	v_add_u32_e32 v4, 1, v4
	s_nop 0
	v_cndmask_b32_e32 v2, v2, v6, vcc
	v_sub_u32_e32 v6, v5, v3
	v_cndmask_b32_e32 v5, v5, v6, vcc
	v_add_u32_e32 v6, 1, v2
	v_cmp_ge_u32_e32 vcc, v5, v3
	s_nop 1
	v_cndmask_b32_e32 v2, v2, v6, vcc
	v_mul_lo_u32 v5, v3, v2
	v_add_u32_e32 v3, v5, v3
	v_cmp_ne_u32_e32 vcc, v4, v3
	s_and_saveexec_b64 s[6:7], vcc
	s_xor_b64 s[6:7], exec, s[6:7]
	s_cbranch_execz .LBB0_425
	s_waitcnt lgkmcnt(0)
	buffer_inv sc1
	v_mov_b32_e32 v1, 0x2000
	global_load_dword v1, v1, s[4:5] offset:1024 sc1
	s_add_u32 s16, s4, 0x2400
	s_addc_u32 s17, s5, 0
	s_waitcnt vmcnt(0)
	v_cmp_eq_u32_e32 vcc, v1, v2
	s_and_saveexec_b64 s[12:13], vcc
	s_cbranch_execz .LBB0_424
	s_add_u32 s14, s28, 0x80200
	s_addc_u32 s15, s29, 0
	s_mov_b32 s38, 1
	s_mov_b64 s[18:19], 0
	v_mov_b32_e32 v1, 0
	s_branch .LBB0_415

; __device__ __forceinline__ unsigned xb_ld(unsigned* p)              { return __hip_atomic_load(p, __ATOMIC_RELAXED, __HIP_MEMORY_SCOPE_AGENT); }
; __device__ __forceinline__ unsigned xb_add(unsigned* p, unsigned v) { return __hip_atomic_fetch_add(p, v, __ATOMIC_RELAXED, __HIP_MEMORY_SCOPE_AGENT); }
; #define XB_SPIN(cond, bar) do { unsigned _sp = 0; while (cond) { __builtin_amdgcn_s_sleep(1); \
;     if ((++_sp & 255u) == 0u) { if (xb_ld(&(bar)[XB_TMO])) break; if (_sp > XB_SPIN_CAP) { atomicAdd(&(bar)[XB_TMO], 1u); break; } } } } while (0)
; __device__ __forceinline__ void xcd_barrier(const XcdBarrier& b) {
;     ...
;         const unsigned old = xb_add(&bar[XB_XSUB(b.x)], 1u);
;         const unsigned gen = old / nloc;
;         if (old + 1u == (gen + 1u) * nloc) {
;             __builtin_amdgcn_fence(__ATOMIC_RELEASE, "agent");
;             asm volatile("s_waitcnt vmcnt(0)" ::: "memory");
;             const unsigned og = xb_add(&bar[XB_TOP], 1u);
;             const unsigned tg = og / nx;
;             if (og + 1u == (tg + 1u) * nx) xb_add(&bar[XB_TOPGEN], 1u);
;             else XB_SPIN(xb_ld(&bar[XB_TOPGEN]) == tg, bar);
;             __builtin_amdgcn_fence(__ATOMIC_ACQUIRE, "agent");
;             xb_add(&bar[XB_XGEN(b.x)], 1u);
;             asm volatile("s_waitcnt vmcnt(0)" ::: "memory");
;         } else {
.LBB0_424:
	s_or_b64 exec, exec, s[12:13]
	s_waitcnt vmcnt(0)
	s_waitcnt vmcnt(0)
.LBB0_425:
	s_andn2_saveexec_b64 s[6:7], s[6:7]
	s_cbranch_execz .LBB0_443
	s_mov_b64 s[6:7], exec
	s_cmp_lg_u32 s98, 0
	s_cbranch_scc1 .Lfast_1
	buffer_inv sc1
	buffer_wbl2 sc1
	s_waitcnt lgkmcnt(0)
	s_waitcnt vmcnt(0)
	v_mbcnt_lo_u32_b32 v2, s6, 0
	v_mbcnt_hi_u32_b32 v2, s7, v2
	v_cmp_eq_u32_e32 vcc, 0, v2
	s_and_saveexec_b64 s[12:13], vcc
	s_cbranch_execz .LBB0_428
	s_bcnt1_i32_b64 s6, s[6:7]
	v_mov_b32_e32 v3, 0x83000
	v_mov_b32_e32 v4, s6
	global_atomic_add v3, v3, v4, s[28:29] offset:1024 sc0

; __device__ __forceinline__ unsigned xb_ld(unsigned* p)              { return __hip_atomic_load(p, __ATOMIC_RELAXED, __HIP_MEMORY_SCOPE_AGENT); }
; __device__ __forceinline__ unsigned xb_add(unsigned* p, unsigned v) { return __hip_atomic_fetch_add(p, v, __ATOMIC_RELAXED, __HIP_MEMORY_SCOPE_AGENT); }
; #define XB_SPIN(cond, bar) do { unsigned _sp = 0; while (cond) { __builtin_amdgcn_s_sleep(1); \
;     if ((++_sp & 255u) == 0u) { if (xb_ld(&(bar)[XB_TMO])) break; if (_sp > XB_SPIN_CAP) { atomicAdd(&(bar)[XB_TMO], 1u); break; } } } } while (0)
; __device__ __forceinline__ void xcd_barrier(const XcdBarrier& b) {
;     ...
;     if (threadIdx.x == 0) {
;         unsigned* bar = b.bar;
;         __builtin_amdgcn_s_waitcnt(0);
;         unsigned nloc = b.st[0], nx = b.st[1];
;         if (nloc == 0u) { xcd_barrier_complete(bar, b.x, nloc, nx); b.st[0] = nloc; b.st[1] = nx; }
;         const unsigned old = xb_add(&bar[XB_XSUB(b.x)], 1u);
;         const unsigned gen = old / nloc;
;         if (old + 1u == (gen + 1u) * nloc) {
;             __builtin_amdgcn_fence(__ATOMIC_RELEASE, "agent");
;             asm volatile("s_waitcnt vmcnt(0)" ::: "memory");
;             const unsigned og = xb_add(&bar[XB_TOP], 1u);
;             const unsigned tg = og / nx;
;             if (og + 1u == (tg + 1u) * nx) xb_add(&bar[XB_TOPGEN], 1u);
;             else XB_SPIN(xb_ld(&bar[XB_TOPGEN]) == tg, bar);
;             __builtin_amdgcn_fence(__ATOMIC_ACQUIRE, "agent");
;             xb_add(&bar[XB_XGEN(b.x)], 1u);
;             asm volatile("s_waitcnt vmcnt(0)" ::: "memory");
;         } else {
;             XB_SPIN(xb_ld(&bar[XB_XGEN(b.x)]) == gen, bar);
.LBB0_522:
	s_lshl_b32 s4, s33, 8
	s_add_u32 s4, s60, s4
	s_addc_u32 s5, s61, 0
	v_mov_b32_e32 v2, 0x1000
	v_mov_b32_e32 v4, 1
	global_atomic_add v4, v2, v4, s[4:5] offset:1024 sc0
	v_cvt_f32_u32_e32 v2, v3
	v_sub_u32_e32 v5, 0, v3
	v_rcp_iflag_f32_e32 v2, v2
	s_nop 0
	v_mul_f32_e32 v2, 0x4f7ffffe, v2
	v_cvt_u32_f32_e32 v2, v2
	v_mul_lo_u32 v5, v5, v2
	v_mul_hi_u32 v5, v2, v5
	v_add_u32_e32 v2, v2, v5
	s_waitcnt vmcnt(0)
	v_mul_hi_u32 v2, v4, v2
	v_mul_lo_u32 v5, v2, v3
	v_sub_u32_e32 v5, v4, v5
	v_add_u32_e32 v6, 1, v2
	v_cmp_ge_u32_e32 vcc, v5, v3
	v_add_u32_e32 v4, 1, v4
	s_nop 0
	v_cndmask_b32_e32 v2, v2, v6, vcc
	v_sub_u32_e32 v6, v5, v3
	v_cndmask_b32_e32 v5, v5, v6, vcc
	v_add_u32_e32 v6, 1, v2
	v_cmp_ge_u32_e32 vcc, v5, v3
	s_nop 1
	v_cndmask_b32_e32 v2, v2, v6, vcc
	v_mul_lo_u32 v5, v3, v2
	v_add_u32_e32 v3, v5, v3
	v_cmp_ne_u32_e32 vcc, v4, v3
	s_and_saveexec_b64 s[6:7], vcc
	s_xor_b64 s[6:7], exec, s[6:7]
	s_cbranch_execz .LBB0_536
	s_waitcnt lgkmcnt(0)
	buffer_inv sc1
	v_mov_b32_e32 v1, 0x2000
	global_load_dword v1, v1, s[4:5] offset:1024 sc1
	s_add_u32 s18, s4, 0x2400
	s_addc_u32 s19, s5, 0
	s_waitcnt vmcnt(0)
	v_cmp_eq_u32_e32 vcc, v1, v2
	s_and_saveexec_b64 s[14:15], vcc
	s_cbranch_execz .LBB0_535
	s_add_u32 s16, s28, 0x80200
	s_addc_u32 s17, s29, 0
	s_mov_b32 s40, 1
	s_mov_b64 s[22:23], 0
	v_mov_b32_e32 v1, 0
	s_branch .LBB0_526

; __device__ __forceinline__ unsigned xb_ld(unsigned* p)              { return __hip_atomic_load(p, __ATOMIC_RELAXED, __HIP_MEMORY_SCOPE_AGENT); }
; __device__ __forceinline__ unsigned xb_add(unsigned* p, unsigned v) { return __hip_atomic_fetch_add(p, v, __ATOMIC_RELAXED, __HIP_MEMORY_SCOPE_AGENT); }
; #define XB_SPIN(cond, bar) do { unsigned _sp = 0; while (cond) { __builtin_amdgcn_s_sleep(1); \
;     if ((++_sp & 255u) == 0u) { if (xb_ld(&(bar)[XB_TMO])) break; if (_sp > XB_SPIN_CAP) { atomicAdd(&(bar)[XB_TMO], 1u); break; } } } } while (0)
; __device__ __forceinline__ void xcd_barrier(const XcdBarrier& b) {
;     ...
;         const unsigned old = xb_add(&bar[XB_XSUB(b.x)], 1u);
;         const unsigned gen = old / nloc;
;         if (old + 1u == (gen + 1u) * nloc) {
;             __builtin_amdgcn_fence(__ATOMIC_RELEASE, "agent");
;             asm volatile("s_waitcnt vmcnt(0)" ::: "memory");
;             const unsigned og = xb_add(&bar[XB_TOP], 1u);
;             const unsigned tg = og / nx;
;             if (og + 1u == (tg + 1u) * nx) xb_add(&bar[XB_TOPGEN], 1u);
;             else XB_SPIN(xb_ld(&bar[XB_TOPGEN]) == tg, bar);
;             __builtin_amdgcn_fence(__ATOMIC_ACQUIRE, "agent");
;             xb_add(&bar[XB_XGEN(b.x)], 1u);
.LBB0_535:
	s_or_b64 exec, exec, s[14:15]
	s_waitcnt vmcnt(0)
	s_waitcnt vmcnt(0)
.LBB0_536:
	s_andn2_saveexec_b64 s[6:7], s[6:7]
	s_cbranch_execz .LBB0_554
	s_mov_b64 s[6:7], exec
	buffer_inv sc1
	buffer_wbl2 sc1
	s_waitcnt lgkmcnt(0)
	s_waitcnt vmcnt(0)
	v_mbcnt_lo_u32_b32 v2, s6, 0
	v_mbcnt_hi_u32_b32 v2, s7, v2
	v_cmp_eq_u32_e32 vcc, 0, v2
	s_and_saveexec_b64 s[14:15], vcc
	s_cbranch_execz .LBB0_539
	s_bcnt1_i32_b64 s6, s[6:7]
	v_mov_b32_e32 v3, 0x83000
	v_mov_b32_e32 v4, s6
	global_atomic_add v3, v3, v4, s[28:29] offset:1024 sc0

; __device__ __forceinline__ unsigned xb_ld(unsigned* p)              { return __hip_atomic_load(p, __ATOMIC_RELAXED, __HIP_MEMORY_SCOPE_AGENT); }
; __device__ __forceinline__ unsigned xb_add(unsigned* p, unsigned v) { return __hip_atomic_fetch_add(p, v, __ATOMIC_RELAXED, __HIP_MEMORY_SCOPE_AGENT); }
; #define XB_SPIN(cond, bar) do { unsigned _sp = 0; while (cond) { __builtin_amdgcn_s_sleep(1); \
;     if ((++_sp & 255u) == 0u) { if (xb_ld(&(bar)[XB_TMO])) break; if (_sp > XB_SPIN_CAP) { atomicAdd(&(bar)[XB_TMO], 1u); break; } } } } while (0)
; __device__ __forceinline__ void xcd_barrier(const XcdBarrier& b) {
;     ...
;             if (og + 1u == (tg + 1u) * nx) xb_add(&bar[XB_TOPGEN], 1u);
;             else XB_SPIN(xb_ld(&bar[XB_TOPGEN]) == tg, bar);
;             __builtin_amdgcn_fence(__ATOMIC_ACQUIRE, "agent");
;             xb_add(&bar[XB_XGEN(b.x)], 1u);
;             asm volatile("s_waitcnt vmcnt(0)" ::: "memory");
.Lfast_8:
	v_mov_b32_e32 v1, 0x2000
	v_mov_b32_e32 v2, 1
	global_atomic_add v1, v2, s[4:5] offset:1024
	buffer_inv sc1
	s_waitcnt vmcnt(0)
	s_branch .LBB0_1314

; __device__ __forceinline__ unsigned xb_ld(unsigned* p)              { return __hip_atomic_load(p, __ATOMIC_RELAXED, __HIP_MEMORY_SCOPE_AGENT); }
; __device__ __forceinline__ unsigned xb_add(unsigned* p, unsigned v) { return __hip_atomic_fetch_add(p, v, __ATOMIC_RELAXED, __HIP_MEMORY_SCOPE_AGENT); }
; #define XB_SPIN(cond, bar) do { unsigned _sp = 0; while (cond) { __builtin_amdgcn_s_sleep(1); \
;     if ((++_sp & 255u) == 0u) { if (xb_ld(&(bar)[XB_TMO])) break; if (_sp > XB_SPIN_CAP) { atomicAdd(&(bar)[XB_TMO], 1u); break; } } } } while (0)
; __device__ __forceinline__ void xcd_barrier(const XcdBarrier& b) {
;     ...
;     if (threadIdx.x == 0) {
;         unsigned* bar = b.bar;
;         __builtin_amdgcn_s_waitcnt(0);
;         unsigned nloc = b.st[0], nx = b.st[1];
;         if (nloc == 0u) { xcd_barrier_complete(bar, b.x, nloc, nx); b.st[0] = nloc; b.st[1] = nx; }
;         const unsigned old = xb_add(&bar[XB_XSUB(b.x)], 1u);
;         const unsigned gen = old / nloc;
;         if (old + 1u == (gen + 1u) * nloc) {
;             __builtin_amdgcn_fence(__ATOMIC_RELEASE, "agent");
;             asm volatile("s_waitcnt vmcnt(0)" ::: "memory");
;             const unsigned og = xb_add(&bar[XB_TOP], 1u);
;             const unsigned tg = og / nx;
;             if (og + 1u == (tg + 1u) * nx) xb_add(&bar[XB_TOPGEN], 1u);
;             else XB_SPIN(xb_ld(&bar[XB_TOPGEN]) == tg, bar);
;             __builtin_amdgcn_fence(__ATOMIC_ACQUIRE, "agent");
;             xb_add(&bar[XB_XGEN(b.x)], 1u);
;             asm volatile("s_waitcnt vmcnt(0)" ::: "memory");
;         } else {
;             XB_SPIN(xb_ld(&bar[XB_XGEN(b.x)]) == gen, bar);
.LBB0_894:
	s_lshl_b32 s4, s33, 8
	s_add_u32 s4, s60, s4
	s_addc_u32 s5, s61, 0
	v_mov_b32_e32 v3, 0x1000
	v_mov_b32_e32 v5, 1
	global_atomic_add v5, v3, v5, s[4:5] offset:1024 sc0
	v_cvt_f32_u32_e32 v3, v4
	v_sub_u32_e32 v6, 0, v4
	v_rcp_iflag_f32_e32 v3, v3
	s_nop 0
	v_mul_f32_e32 v3, 0x4f7ffffe, v3
	v_cvt_u32_f32_e32 v3, v3
	v_mul_lo_u32 v6, v6, v3
	v_mul_hi_u32 v6, v3, v6
	v_add_u32_e32 v3, v3, v6
	s_waitcnt vmcnt(0)
	v_mul_hi_u32 v3, v5, v3
	v_mul_lo_u32 v6, v3, v4
	v_sub_u32_e32 v6, v5, v6
	v_add_u32_e32 v7, 1, v3
	v_cmp_ge_u32_e32 vcc, v6, v4
	v_add_u32_e32 v5, 1, v5
	s_nop 0
	v_cndmask_b32_e32 v3, v3, v7, vcc
	v_sub_u32_e32 v7, v6, v4
	v_cndmask_b32_e32 v6, v6, v7, vcc
	v_add_u32_e32 v7, 1, v3
	v_cmp_ge_u32_e32 vcc, v6, v4
	s_nop 1
	v_cndmask_b32_e32 v3, v3, v7, vcc
	v_mul_lo_u32 v6, v4, v3
	v_add_u32_e32 v4, v6, v4
	v_cmp_ne_u32_e32 vcc, v5, v4
	s_and_saveexec_b64 s[6:7], vcc
	s_xor_b64 s[6:7], exec, s[6:7]
	s_cbranch_execz .LBB0_908
	s_waitcnt lgkmcnt(0)
	buffer_inv sc1
	v_mov_b32_e32 v2, 0x2000
	global_load_dword v2, v2, s[4:5] offset:1024 sc1
	s_add_u32 s16, s4, 0x2400
	s_addc_u32 s17, s5, 0
	s_waitcnt vmcnt(0)
	v_cmp_eq_u32_e32 vcc, v2, v3
	s_and_saveexec_b64 s[12:13], vcc
	s_cbranch_execz .LBB0_907
	s_add_u32 s14, s28, 0x80200
	s_addc_u32 s15, s29, 0
	s_mov_b32 s38, 1
	s_mov_b64 s[18:19], 0
	v_mov_b32_e32 v2, 0
	s_branch .LBB0_898

; __device__ __forceinline__ unsigned xb_ld(unsigned* p)              { return __hip_atomic_load(p, __ATOMIC_RELAXED, __HIP_MEMORY_SCOPE_AGENT); }
; __device__ __forceinline__ unsigned xb_add(unsigned* p, unsigned v) { return __hip_atomic_fetch_add(p, v, __ATOMIC_RELAXED, __HIP_MEMORY_SCOPE_AGENT); }
; #define XB_SPIN(cond, bar) do { unsigned _sp = 0; while (cond) { __builtin_amdgcn_s_sleep(1); \
;     if ((++_sp & 255u) == 0u) { if (xb_ld(&(bar)[XB_TMO])) break; if (_sp > XB_SPIN_CAP) { atomicAdd(&(bar)[XB_TMO], 1u); break; } } } } while (0)
; __device__ __forceinline__ void xcd_barrier(const XcdBarrier& b) {
;     ...
;         const unsigned old = xb_add(&bar[XB_XSUB(b.x)], 1u);
;         const unsigned gen = old / nloc;
;         if (old + 1u == (gen + 1u) * nloc) {
;             __builtin_amdgcn_fence(__ATOMIC_RELEASE, "agent");
;             asm volatile("s_waitcnt vmcnt(0)" ::: "memory");
;             const unsigned og = xb_add(&bar[XB_TOP], 1u);
;             const unsigned tg = og / nx;
;             if (og + 1u == (tg + 1u) * nx) xb_add(&bar[XB_TOPGEN], 1u);
;             else XB_SPIN(xb_ld(&bar[XB_TOPGEN]) == tg, bar);
;             __builtin_amdgcn_fence(__ATOMIC_ACQUIRE, "agent");
;             xb_add(&bar[XB_XGEN(b.x)], 1u);
.LBB0_908:
	s_andn2_saveexec_b64 s[6:7], s[6:7]
	s_cbranch_execz .LBB0_926
	s_mov_b64 s[6:7], exec
	buffer_inv sc1
	buffer_wbl2 sc1
	s_waitcnt lgkmcnt(0)
	s_waitcnt vmcnt(0)
	v_mbcnt_lo_u32_b32 v3, s6, 0
	v_mbcnt_hi_u32_b32 v3, s7, v3
	v_cmp_eq_u32_e32 vcc, 0, v3
	s_and_saveexec_b64 s[12:13], vcc
	s_cbranch_execz .LBB0_911
	s_bcnt1_i32_b64 s6, s[6:7]
	v_mov_b32_e32 v4, 0x83000
	v_mov_b32_e32 v5, s6
	global_atomic_add v4, v4, v5, s[28:29] offset:1024 sc0

; __device__ __forceinline__ unsigned xb_ld(unsigned* p)              { return __hip_atomic_load(p, __ATOMIC_RELAXED, __HIP_MEMORY_SCOPE_AGENT); }
; __device__ __forceinline__ unsigned xb_add(unsigned* p, unsigned v) { return __hip_atomic_fetch_add(p, v, __ATOMIC_RELAXED, __HIP_MEMORY_SCOPE_AGENT); }
; #define XB_SPIN(cond, bar) do { unsigned _sp = 0; while (cond) { __builtin_amdgcn_s_sleep(1); \
;     if ((++_sp & 255u) == 0u) { if (xb_ld(&(bar)[XB_TMO])) break; if (_sp > XB_SPIN_CAP) { atomicAdd(&(bar)[XB_TMO], 1u); break; } } } } while (0)
; __device__ __forceinline__ void xcd_barrier(const XcdBarrier& b) {
;     ...
;     if (threadIdx.x == 0) {
;         unsigned* bar = b.bar;
;         __builtin_amdgcn_s_waitcnt(0);
;         unsigned nloc = b.st[0], nx = b.st[1];
;         if (nloc == 0u) { xcd_barrier_complete(bar, b.x, nloc, nx); b.st[0] = nloc; b.st[1] = nx; }
;         const unsigned old = xb_add(&bar[XB_XSUB(b.x)], 1u);
;         const unsigned gen = old / nloc;
;         if (old + 1u == (gen + 1u) * nloc) {
;             __builtin_amdgcn_fence(__ATOMIC_RELEASE, "agent");
;             asm volatile("s_waitcnt vmcnt(0)" ::: "memory");
;             const unsigned og = xb_add(&bar[XB_TOP], 1u);
;             const unsigned tg = og / nx;
;             if (og + 1u == (tg + 1u) * nx) xb_add(&bar[XB_TOPGEN], 1u);
;             else XB_SPIN(xb_ld(&bar[XB_TOPGEN]) == tg, bar);
;             __builtin_amdgcn_fence(__ATOMIC_ACQUIRE, "agent");
;             xb_add(&bar[XB_XGEN(b.x)], 1u);
;             asm volatile("s_waitcnt vmcnt(0)" ::: "memory");
;         } else {
;             XB_SPIN(xb_ld(&bar[XB_XGEN(b.x)]) == gen, bar);
.LBB0_1282:
	s_lshl_b32 s4, s33, 8
	s_add_u32 s4, s60, s4
	s_addc_u32 s5, s61, 0
	v_mov_b32_e32 v2, 0x1000
	v_mov_b32_e32 v4, 1
	global_atomic_add v4, v2, v4, s[4:5] offset:1024 sc0
	v_cvt_f32_u32_e32 v2, v3
	v_sub_u32_e32 v5, 0, v3
	v_rcp_iflag_f32_e32 v2, v2
	s_nop 0
	v_mul_f32_e32 v2, 0x4f7ffffe, v2
	v_cvt_u32_f32_e32 v2, v2
	v_mul_lo_u32 v5, v5, v2
	v_mul_hi_u32 v5, v2, v5
	v_add_u32_e32 v2, v2, v5
	s_waitcnt vmcnt(0)
	v_mul_hi_u32 v2, v4, v2
	v_mul_lo_u32 v5, v2, v3
	v_sub_u32_e32 v5, v4, v5
	v_add_u32_e32 v6, 1, v2
	v_cmp_ge_u32_e32 vcc, v5, v3
	v_add_u32_e32 v4, 1, v4
	s_nop 0
	v_cndmask_b32_e32 v2, v2, v6, vcc
	v_sub_u32_e32 v6, v5, v3
	v_cndmask_b32_e32 v5, v5, v6, vcc
	v_add_u32_e32 v6, 1, v2
	v_cmp_ge_u32_e32 vcc, v5, v3
	s_nop 1
	v_cndmask_b32_e32 v2, v2, v6, vcc
	v_mul_lo_u32 v5, v3, v2
	v_add_u32_e32 v3, v5, v3
	v_cmp_ne_u32_e32 vcc, v4, v3
	s_and_saveexec_b64 s[6:7], vcc
	s_xor_b64 s[6:7], exec, s[6:7]
	s_cbranch_execz .LBB0_1296
	s_waitcnt lgkmcnt(0)
	buffer_inv sc1
	v_mov_b32_e32 v1, 0x2000
	global_load_dword v1, v1, s[4:5] offset:1024 sc1
	s_add_u32 s16, s4, 0x2400
	s_addc_u32 s17, s5, 0
	s_waitcnt vmcnt(0)
	v_cmp_eq_u32_e32 vcc, v1, v2
	s_and_saveexec_b64 s[12:13], vcc
	s_cbranch_execz .LBB0_1295
	s_add_u32 s14, s28, 0x80200
	s_addc_u32 s15, s29, 0
	s_mov_b32 s33, 1
	s_mov_b64 s[18:19], 0
	v_mov_b32_e32 v1, 0
	s_branch .LBB0_1286

; __global__ void __launch_bounds__(NTHREADS, 2) mega_fwd(Args a) {
	.amdhsa_kernel _Z8mega_fwd4Args
		.amdhsa_group_segment_fixed_size 0
		.amdhsa_private_segment_fixed_size 0
		.amdhsa_kernarg_size 608
		.amdhsa_user_sgpr_count 2
		.amdhsa_user_sgpr_dispatch_ptr 0
		.amdhsa_user_sgpr_queue_ptr 0
		.amdhsa_user_sgpr_kernarg_segment_ptr 1
		.amdhsa_user_sgpr_dispatch_id 0
		.amdhsa_user_sgpr_kernarg_preload_length 0
		.amdhsa_user_sgpr_kernarg_preload_offset 0
		.amdhsa_user_sgpr_private_segment_size 0
		.amdhsa_uses_dynamic_stack 0
		.amdhsa_enable_private_segment 0
		.amdhsa_system_sgpr_workgroup_id_x 1
		.amdhsa_system_sgpr_workgroup_id_y 0
		.amdhsa_system_sgpr_workgroup_id_z 0
		.amdhsa_system_sgpr_workgroup_info 0
		.amdhsa_system_vgpr_workitem_id 2
		.amdhsa_next_free_vgpr 246
		.amdhsa_next_free_sgpr 102
		.amdhsa_accum_offset 248
		.amdhsa_reserve_vcc 1
		.amdhsa_float_round_mode_32 0
		.amdhsa_float_round_mode_16_64 0
		.amdhsa_float_denorm_mode_32 3
		.amdhsa_float_denorm_mode_16_64 3
		.amdhsa_dx10_clamp 1
		.amdhsa_ieee_mode 1
		.amdhsa_fp16_overflow 0
		.amdhsa_tg_split 0
		.amdhsa_exception_fp_ieee_invalid_op 0
		.amdhsa_exception_fp_denorm_src 0
		.amdhsa_exception_fp_ieee_div_zero 0
		.amdhsa_exception_fp_ieee_overflow 0
		.amdhsa_exception_fp_ieee_underflow 0
		.amdhsa_exception_fp_ieee_inexact 0
		.amdhsa_exception_int_div_zero 0
	.end_amdhsa_kernel

; __global__ void __launch_bounds__(NTHREADS, 2) mega_fwd(Args a) {
amdhsa.kernels:
  - .agpr_count:     0
    .args:
      - .offset:         0
        .size:           352
        .value_kind:     by_value
      - .offset:         352
        .size:           4
        .value_kind:     hidden_block_count_x
      - .offset:         356
        .size:           4
        .value_kind:     hidden_block_count_y
      - .offset:         360
        .size:           4
        .value_kind:     hidden_block_count_z
      - .offset:         364
        .size:           2
        .value_kind:     hidden_group_size_x
      - .offset:         366
        .size:           2
        .value_kind:     hidden_group_size_y
      - .offset:         368
        .size:           2
        .value_kind:     hidden_group_size_z
      - .offset:         370
        .size:           2
        .value_kind:     hidden_remainder_x
      - .offset:         372
        .size:           2
        .value_kind:     hidden_remainder_y
      - .offset:         374
        .size:           2
        .value_kind:     hidden_remainder_z
      - .offset:         392
        .size:           8
        .value_kind:     hidden_global_offset_x
      - .offset:         400
        .size:           8
        .value_kind:     hidden_global_offset_y
      - .offset:         408
        .size:           8
        .value_kind:     hidden_global_offset_z
      - .offset:         416
        .size:           2
        .value_kind:     hidden_grid_dims
      - .offset:         440
        .size:           8
        .value_kind:     hidden_multigrid_sync_arg
      - .offset:         472
        .size:           4
        .value_kind:     hidden_dynamic_lds_size
    .group_segment_fixed_size: 0
    .kernarg_segment_align: 8
    .kernarg_segment_size: 608
    .language:       OpenCL C
    .language_version:
      - 2
      - 0
    .max_flat_workgroup_size: 512
    .name:           _Z8mega_fwd4Args
    .private_segment_fixed_size: 0
    .sgpr_count:     108
    .sgpr_spill_count: 6
    .symbol:         _Z8mega_fwd4Args.kd
    .uniform_work_group_size: 1
    .uses_dynamic_stack: false
    .vgpr_count:     246
    .vgpr_spill_count: 0
    .wavefront_size: 64
